# MoBA kmean loop: 16 row loads per iteration issued together with counted vmcnt, same summation order (was load/wait/add x16)
# speedup vs baseline: 1.0056x; 1.0056x over previous
; DI int otid() { int t = threadIdx.x; asm volatile("" : "+v"(t)); return t; }
; DI void kmean_item(const Params& P0_, int item, uchar* smem) {
;   const KP P = kparams();
;   const u16* H = (const u16*)(P.ws() + OFF_H);
;   float* KM = (float*)(P.ws() + OFF_KM);
;   const int tid = otid(), lane = tid & 63, wave = tid >> 6;
;   const int b = item >> 4, blk = item & 15;
;   float* part = (float*)smem;
;   float a0 = 0.f, a1 = 0.f, a2 = 0.f, a3 = 0.f;
;   const u16* p = H + ((size_t)b * SL + blk * 256 + wave * 64) * HC + C_K + lane * 4;
; #pragma unroll 16
;   for (int t = 0; t < 64; ++t) {
.LBB0_209:
	s_and_b64 vcc, exec, s[0:1]
	s_cbranch_vccz .LBB0_213
	s_add_i32 s16, s38, 0xfffffcd0
	v_readlane_b32 s6, v253, 57
	s_mov_b64 s[0:1], s[54:55]
	v_readlane_b32 s7, v253, 58
	s_lshr_b32 s6, s16, 4
	s_waitcnt vmcnt(62)
	v_mov_b32_e32 v6, v166
	v_writelane_b32 v253, s6, 57
	s_lshl_b32 s16, s16, 8
	s_load_dwordx2 s[0:1], s[0:1], 0xe8
	v_writelane_b32 v253, s7, 58
	s_lshl_b64 s[6:7], s[6:7], 12
	s_and_b32 s16, s16, 0xf00
	v_and_b32_e32 v2, 0xffffffc0, v6
	s_or_b32 s6, s6, s16
	v_ashrrev_i32_e32 v3, 31, v2
	v_lshl_add_u64 v[2:3], s[6:7], 0, v[2:3]
	v_mad_u64_u32 v[4:5], s[6:7], v2, s33, 0
	v_and_b32_e32 v0, 63, v6
	v_mad_i32_i24 v3, v3, s33, v5
	v_lshl_or_b32 v2, v0, 3, v4
	s_waitcnt vmcnt(61) lgkmcnt(0)
	v_lshl_add_u64 v[8:9], s[0:1], 0, v[2:3]
	v_mov_b32_e32 v2, 0
	s_mov_b64 s[6:7], 0
	v_mov_b32_e32 v3, v2
	v_mov_b32_e32 v4, v2
	v_mov_b32_e32 v5, v2
	s_waitcnt vmcnt(0)
; DI float bflo(unsigned v) { return __uint_as_float(v << 16); }
; DI float bfhi(unsigned v) { return __uint_as_float(v & 0xffff0000u); }
; DI void kmean_item(const Params& P0_, int item, uchar* smem) {
;     ...
; #pragma unroll 16
;   for (int t = 0; t < 64; ++t) {
;     uint2 v = *(const uint2*)(p + (size_t)t * HC);
;     a0 += bflo(v.x); a1 += bfhi(v.x); a2 += bflo(v.y); a3 += bfhi(v.y);
;   }
;   __syncthreads();
;   part[wave * 256 + lane * 4 + 0] = a0; part[wave * 256 + lane * 4 + 1] = a1; part[wave * 256 + lane * 4 + 2] = a2; part[wave * 256 + lane * 4 + 3] = a3;
;   __syncthreads();
;   KM[((size_t)b * 16 + blk) * 256 + tid] = (part[tid] + part[256 + tid] + part[512 + tid] + part[768 + tid]) * (1.f / 256.f);
.LBB0_211:
	v_lshl_add_u64 v[10:11], v[8:9], 0, s[6:7]
	s_mov_b32 s101, 0
	s_mov_b32 s100, 0x6101f80
	v_lshl_add_u64 v[72:73], v[10:11], 0, s[100:101]
	global_load_dwordx2 v[40:41], v[72:73], off offset:-3584
	global_load_dwordx2 v[42:43], v[72:73], off offset:3584
	s_mov_b32 s100, 0x6105780
	v_lshl_add_u64 v[74:75], v[10:11], 0, s[100:101]
	global_load_dwordx2 v[44:45], v[74:75], off offset:-3584
	global_load_dwordx2 v[46:47], v[74:75], off offset:3584
	s_mov_b32 s100, 0x6108f80
	v_lshl_add_u64 v[76:77], v[10:11], 0, s[100:101]
	global_load_dwordx2 v[48:49], v[76:77], off offset:-3584
	global_load_dwordx2 v[50:51], v[76:77], off offset:3584
	s_mov_b32 s100, 0x610c780
	v_lshl_add_u64 v[78:79], v[10:11], 0, s[100:101]
	global_load_dwordx2 v[52:53], v[78:79], off offset:-3584
	global_load_dwordx2 v[54:55], v[78:79], off offset:3584
	s_mov_b32 s100, 0x610ff80
	v_lshl_add_u64 v[80:81], v[10:11], 0, s[100:101]
	global_load_dwordx2 v[56:57], v[80:81], off offset:-3584
	global_load_dwordx2 v[58:59], v[80:81], off offset:3584
	s_mov_b32 s100, 0x6113780
	v_lshl_add_u64 v[82:83], v[10:11], 0, s[100:101]
	global_load_dwordx2 v[60:61], v[82:83], off offset:-3584
	global_load_dwordx2 v[62:63], v[82:83], off offset:3584
	s_mov_b32 s100, 0x6116f80
	v_lshl_add_u64 v[84:85], v[10:11], 0, s[100:101]
	global_load_dwordx2 v[64:65], v[84:85], off offset:-3584
	global_load_dwordx2 v[66:67], v[84:85], off offset:3584
	s_mov_b32 s100, 0x611a780
	v_lshl_add_u64 v[86:87], v[10:11], 0, s[100:101]
	global_load_dwordx2 v[68:69], v[86:87], off offset:-3584
	global_load_dwordx2 v[70:71], v[86:87], off offset:3584
	s_waitcnt vmcnt(15)
	v_lshlrev_b32_e32 v14, 16, v40
	v_and_b32_e32 v15, 0xffff0000, v40
	v_lshlrev_b32_e32 v12, 16, v41
	v_and_b32_e32 v13, 0xffff0000, v41
	v_pk_add_f32 v[4:5], v[4:5], v[12:13]
	v_pk_add_f32 v[2:3], v[2:3], v[14:15]
	s_waitcnt vmcnt(14)
	v_lshlrev_b32_e32 v14, 16, v42
	v_and_b32_e32 v15, 0xffff0000, v42
	v_lshlrev_b32_e32 v12, 16, v43
	v_and_b32_e32 v13, 0xffff0000, v43
	v_pk_add_f32 v[4:5], v[4:5], v[12:13]
	v_pk_add_f32 v[2:3], v[2:3], v[14:15]
	s_waitcnt vmcnt(13)
	v_lshlrev_b32_e32 v14, 16, v44
	v_and_b32_e32 v15, 0xffff0000, v44
	v_lshlrev_b32_e32 v12, 16, v45
	v_and_b32_e32 v13, 0xffff0000, v45
	v_pk_add_f32 v[4:5], v[4:5], v[12:13]
	v_pk_add_f32 v[2:3], v[2:3], v[14:15]
	s_waitcnt vmcnt(12)
	v_lshlrev_b32_e32 v14, 16, v46
	v_and_b32_e32 v15, 0xffff0000, v46
	v_lshlrev_b32_e32 v12, 16, v47
	v_and_b32_e32 v13, 0xffff0000, v47
	v_pk_add_f32 v[4:5], v[4:5], v[12:13]
	v_pk_add_f32 v[2:3], v[2:3], v[14:15]
	s_waitcnt vmcnt(11)
	v_lshlrev_b32_e32 v14, 16, v48
	v_and_b32_e32 v15, 0xffff0000, v48
	v_lshlrev_b32_e32 v12, 16, v49
	v_and_b32_e32 v13, 0xffff0000, v49
	v_pk_add_f32 v[4:5], v[4:5], v[12:13]
	v_pk_add_f32 v[2:3], v[2:3], v[14:15]
	s_waitcnt vmcnt(10)
	v_lshlrev_b32_e32 v14, 16, v50
	v_and_b32_e32 v15, 0xffff0000, v50
	v_lshlrev_b32_e32 v12, 16, v51
	v_and_b32_e32 v13, 0xffff0000, v51
	v_pk_add_f32 v[4:5], v[4:5], v[12:13]
	v_pk_add_f32 v[2:3], v[2:3], v[14:15]
	s_waitcnt vmcnt(9)
	v_lshlrev_b32_e32 v14, 16, v52
	v_and_b32_e32 v15, 0xffff0000, v52
	v_lshlrev_b32_e32 v12, 16, v53
	v_and_b32_e32 v13, 0xffff0000, v53
	v_pk_add_f32 v[4:5], v[4:5], v[12:13]
	v_pk_add_f32 v[2:3], v[2:3], v[14:15]
	s_waitcnt vmcnt(8)
	v_lshlrev_b32_e32 v14, 16, v54
	v_and_b32_e32 v15, 0xffff0000, v54
	v_lshlrev_b32_e32 v12, 16, v55
	v_and_b32_e32 v13, 0xffff0000, v55
	v_pk_add_f32 v[4:5], v[4:5], v[12:13]
	v_pk_add_f32 v[2:3], v[2:3], v[14:15]
	s_waitcnt vmcnt(7)
	v_lshlrev_b32_e32 v14, 16, v56
	v_and_b32_e32 v15, 0xffff0000, v56
	v_lshlrev_b32_e32 v12, 16, v57
	v_and_b32_e32 v13, 0xffff0000, v57
	v_pk_add_f32 v[4:5], v[4:5], v[12:13]
	v_pk_add_f32 v[2:3], v[2:3], v[14:15]
	s_waitcnt vmcnt(6)
	v_lshlrev_b32_e32 v14, 16, v58
	v_and_b32_e32 v15, 0xffff0000, v58
	v_lshlrev_b32_e32 v12, 16, v59
	v_and_b32_e32 v13, 0xffff0000, v59
	v_pk_add_f32 v[4:5], v[4:5], v[12:13]
	v_pk_add_f32 v[2:3], v[2:3], v[14:15]
	s_waitcnt vmcnt(5)
	v_lshlrev_b32_e32 v14, 16, v60
	v_and_b32_e32 v15, 0xffff0000, v60
	v_lshlrev_b32_e32 v12, 16, v61
	v_and_b32_e32 v13, 0xffff0000, v61
	v_pk_add_f32 v[4:5], v[4:5], v[12:13]
	v_pk_add_f32 v[2:3], v[2:3], v[14:15]
	s_waitcnt vmcnt(4)
	v_lshlrev_b32_e32 v14, 16, v62
	v_and_b32_e32 v15, 0xffff0000, v62
	v_lshlrev_b32_e32 v12, 16, v63
	v_and_b32_e32 v13, 0xffff0000, v63
	v_pk_add_f32 v[4:5], v[4:5], v[12:13]
	v_pk_add_f32 v[2:3], v[2:3], v[14:15]
	s_waitcnt vmcnt(3)
	v_lshlrev_b32_e32 v14, 16, v64
	v_and_b32_e32 v15, 0xffff0000, v64
	v_lshlrev_b32_e32 v12, 16, v65
	v_and_b32_e32 v13, 0xffff0000, v65
	v_pk_add_f32 v[4:5], v[4:5], v[12:13]
	v_pk_add_f32 v[2:3], v[2:3], v[14:15]
	s_waitcnt vmcnt(2)
	v_lshlrev_b32_e32 v14, 16, v66
	v_and_b32_e32 v15, 0xffff0000, v66
	v_lshlrev_b32_e32 v12, 16, v67
	v_and_b32_e32 v13, 0xffff0000, v67
	v_pk_add_f32 v[4:5], v[4:5], v[12:13]
	v_pk_add_f32 v[2:3], v[2:3], v[14:15]
	s_waitcnt vmcnt(1)
	v_lshlrev_b32_e32 v14, 16, v68
	v_and_b32_e32 v15, 0xffff0000, v68
	v_lshlrev_b32_e32 v12, 16, v69
	v_and_b32_e32 v13, 0xffff0000, v69
	v_pk_add_f32 v[4:5], v[4:5], v[12:13]
	v_pk_add_f32 v[2:3], v[2:3], v[14:15]
	s_waitcnt vmcnt(0)
	v_lshlrev_b32_e32 v14, 16, v70
	v_and_b32_e32 v15, 0xffff0000, v70
	v_lshlrev_b32_e32 v12, 16, v71
	v_and_b32_e32 v13, 0xffff0000, v71
	v_pk_add_f32 v[4:5], v[4:5], v[12:13]
	v_pk_add_f32 v[2:3], v[2:3], v[14:15]
	s_mov_b32 s17, 0x611b000
	s_add_u32 s6, s6, 0x1c000
	s_addc_u32 s7, s7, 0
	s_cmp_lg_u32 s6, 0x70000
	s_cbranch_scc1 .LBB0_211
	v_readlane_b32 s6, v253, 57
	v_lshlrev_b32_e32 v0, 2, v6
	v_lshlrev_b32_e32 v7, 4, v6
	v_readlane_b32 s7, v253, 58
	s_barrier
	ds_write_b128 v7, v[2:5]
	s_waitcnt lgkmcnt(0)
	s_barrier
	ds_read2st64_b32 v[2:3], v0 offset1:4
	ds_read2st64_b32 v[4:5], v0 offset0:8 offset1:12
	s_lshl_b64 s[6:7], s[6:7], 14
	s_add_u32 s0, s0, s6
	s_addc_u32 s1, s1, s7
	s_lshl_b32 s6, s16, 2
	s_add_u32 s0, s0, s6
	v_ashrrev_i32_e32 v7, 31, v6
	s_waitcnt lgkmcnt(1)
	v_add_f32_e32 v0, v2, v3
	s_addc_u32 s1, s1, 0
	s_waitcnt lgkmcnt(0)
	v_add_f32_e32 v0, v0, v4
	v_lshl_add_u64 v[2:3], v[6:7], 2, s[0:1]
	v_add_f32_e32 v0, v0, v5
	v_add_co_u32_e32 v2, vcc, 0x1ad80000, v2
	v_mul_f32_e32 v0, 0x3b800000, v0
	s_nop 0
	v_addc_co_u32_e32 v3, vcc, 0, v3, vcc
	global_store_dword v[2:3], v0, off
